# phase-0 transpose items re-dealt 16 per adaLN workgroup / 36 per free workgroup, now that the adaLN workgroups' pool-fold fetch is hidden
# speedup vs baseline: 1.0018x; 1.0003x over previous
.LBB0_29:
	s_lshr_b32 s94, s93, 6
	s_lshl_b32 s0, s24, 3
	s_add_i32 s8, s0, s94
	s_lshl_b32 s3, s56, 3
	s_lshl_b32 s66, s56, 9
	s_add_u32 s6, s54, 0x500000
	s_addc_u32 s7, s55, 0
	s_add_u32 s64, s54, 0x900000
	s_addc_u32 s65, s55, 0
	s_add_u32 s60, s54, 0xb00000
	s_addc_u32 s61, s55, 0
	s_add_u32 s50, s54, 0x1300000
	s_addc_u32 s51, s55, 0
	s_cmp_lt_i32 s40, 1
	v_writelane_b32 v246, s24, 6
	s_cselect_b64 s[4:5], -1, 0
	s_cmp_gt_i32 s40, 0
	v_writelane_b32 v246, s0, 7
	s_cselect_b64 s[0:1], -1, 0
	s_cmp_lt_i32 s41, 1
	s_cselect_b64 s[10:11], -1, 0
	s_or_b64 s[0:1], s[10:11], s[0:1]
	s_and_b64 vcc, exec, s[0:1]
	s_cbranch_vccnz .LBB0_71
	v_mov_b32_e32 v1, 0
	v_mbcnt_lo_u32_b32 v163, -1, 0
	v_mbcnt_hi_u32_b32 v163, -1, v163
	s_cmpk_gt_i32 s8, 0x14ff
	s_waitcnt vmcnt(3)
	v_readlane_b32 s13, v247, 29
	v_readlane_b32 s12, v247, 28
	s_waitcnt vmcnt(2)
	v_readlane_b32 s11, v247, 37
	v_readlane_b32 s10, v247, 36
	s_waitcnt vmcnt(1)
	v_readlane_b32 s15, v247, 25
	v_readlane_b32 s14, v247, 24
	s_waitcnt vmcnt(0)
	v_readlane_b32 s17, v247, 27
	v_readlane_b32 s16, v247, 26
	v_lshrrev_b32_e32 v3, 3, v163
	v_and_b32_e32 v2, 7, v163
	v_lshlrev_b32_e32 v4, 4, v2
	s_lshl_b32 s18, s94, 14
	v_mul_u32_u24_e32 v5, 33, v3
	v_lshl_add_u32 v5, v2, 2, v5
	v_lshl_add_u32 v5, v5, 2, s18
	v_mul_u32_u24_e32 v6, 0x108, v2
	v_add_u32_e32 v6, v6, v3
	v_lshl_add_u32 v6, v6, 2, s18
	s_lshr_b32 s18, s8, 3
	s_cmp_lg_u32 s56, 0x100
	s_cbranch_scc1 .Ltr_generic
	s_cmp_lt_u32 s18, 0xc0
	s_cbranch_scc0 .Ltr_free
	s_mul_i32 s0, s18, 16
	s_add_i32 s9, s0, 16
	s_branch .Ltr_dealt
